# token-prep phase: the second workgroup of each CU pair (id >= 256) runs the 16-token tile part first and the per-token row part last, so the latency-bound and the VALU-bound parts of the two co-reside
# speedup vs baseline: 1.0002x; 1.0002x over previous
; #define LAUNDER_IDS const int tid__ = launder_v((int)threadIdx.x); const int blk__ = launder_s((int)blockIdx.x); (void)tid__; (void)blk__;
; DI void phase_tokA(const Params& p, int l) {
;   LAUNDER_IDS
;   const int wave = tid__ >> 6, lane = tid__ & 63;
;   const u16* za = (const u16*)(p.ws + OFF_R2);
;   float* rsq = (float*)(p.ws + OFF_RSQ); float* rskv = (float*)(p.ws + OFF_RSKV);
;   u16* krb = (u16*)(p.ws + OFF_KR);
;   u16* pooled = (u16*)(p.ws + OFF_R4);
;   const float* rt = (const float*)(p.ws + OFF_ROPE);
;   const float* gk = p.in[I_GK] + l * 96;
;   for (int r = blk__ * 4 + wave; r < NT; r += gridDim.x * 4) {
;     const u16* z = za + (size_t)r * ZA;
;     const bool lat = r < NTL;
;     const int b = lat ? r >> 12 : (r - NTL) >> 8;
;     const int t = lat ? r & 4095 : (r - NTL) & 255;
;     const int Ls = lat ? L : LC;
;     const int pos = lat ? t : 4096 + t;
;     u16 zq[6], zk[4], pw[30], pc[4];
; #pragma unroll
;     for (int i = 0; i < 6; ++i) zq[i] = z[256 + i * 64 + lane];
; #pragma unroll
;     for (int i = 0; i < 4; ++i) zk[i] = z[640 + i * 64 + lane];
;     const int d = lane & 31;
;     const u16 kr_raw = z[896 + d];
;     const float gkd = gk[64 + d];
;     const int ri = d & 15;
;     const int pp = ri < 8 ? (t >> 6) : (t & 63);
;     const float cs = rt[(pp * 8 + (ri & 7)) * 2], sn = rt[(pp * 8 + (ri & 7)) * 2 + 1];
.LBB0_754:
	s_mov_b32 s101, 0
	s_andn2_b64 vcc, exec, s[0:1]
	s_cbranch_vccnz .LBB0_847
.Ltok_again:
	v_mov_b32_e32 v3, v163
	s_mov_b32 s0, s2
	s_nop 0
	v_ashrrev_i32_e32 v0, 6, v3
	v_lshl_add_u32 v2, s0, 2, v0
	s_mov_b32 s0, 0x8800
	v_cmp_gt_i32_e32 vcc, s0, v2
	s_and_saveexec_b64 s[26:27], vcc
	s_mov_b32 s38, 0x3b2aaaab
	v_readlane_b32 s42, v254, 63
	v_readlane_b32 s36, v253, 33
	s_movk_i32 s37, 0xc00
	s_mov_b32 s39, 0x3b800000
	s_movk_i32 s40, 0x900
	v_readlane_b32 s43, v255, 0
	v_readlane_b32 s41, v254, 57
	s_cmp_eq_u32 s101, 2
	s_cbranch_scc1 .Ltok_do_a
	s_cmpk_lt_i32 s2, 0x100
	s_cbranch_scc1 .Ltok_do_a
	s_mov_b32 s101, 1
	s_branch .LBB0_762
.Ltok_do_a:
	s_cbranch_execz .LBB0_762
	s_waitcnt vmcnt(0)
	v_and_b32_e32 v12, 31, v3
	v_readlane_b32 s0, v254, 33
	v_lshlrev_b32_e32 v0, 2, v12
	v_readlane_b32 s1, v254, 34
	v_and_b32_e32 v6, 64, v237
	v_and_b32_e32 v10, 63, v3
	v_lshl_add_u64 v[4:5], s[0:1], 0, v[0:1]
	v_and_b32_e32 v0, 8, v3
	v_cmp_eq_u32_e64 s[0:1], 0, v0
	v_lshlrev_b32_e32 v0, 1, v3
	v_and_b32_e32 v3, 14, v0
	v_xor_b32_e32 v0, 16, v237
	v_add_u32_e32 v6, 64, v6
	v_cmp_lt_i32_e32 vcc, v0, v6
	v_readlane_b32 s8, v254, 39
	v_readlane_b32 s9, v254, 40
	v_cndmask_b32_e32 v0, v237, v0, vcc
	v_lshlrev_b32_e32 v32, 2, v0
	v_lshlrev_b32_e32 v0, 1, v12
	v_lshl_add_u64 v[6:7], s[8:9], 0, v[0:1]
	v_readlane_b32 s8, v254, 41
	v_lshlrev_b32_e32 v0, 1, v10
	v_readlane_b32 s9, v254, 42
	v_cmp_gt_u32_e64 s[16:17], 16, v12
	v_cmp_eq_u32_e64 s[4:5], 0, v10
	v_cmp_gt_u32_e64 s[6:7], 32, v10
	v_lshl_add_u64 v[8:9], s[8:9], 0, v[0:1]
	s_mov_b64 s[28:29], 0
	v_lshlrev_b32_e32 v0, 1, v10
	v_lshlrev_b32_e32 v10, 1, v12
	v_lshlrev_b32_e32 v33, 2, v3
	s_branch .LBB0_758

; #define LAUNDER_IDS const int tid__ = launder_v((int)threadIdx.x); const int blk__ = launder_s((int)blockIdx.x); (void)tid__; (void)blk__;
; DI void phase_tokB(const Params& p, int l, char* smem) {
;   LAUNDER_IDS
;   WAVE_COORDS
;   const int tid = tid__;
;   u16* Zs = (u16*)smem;
;   u16* TA = Zs + 18 * ZSL;
;   float* PV = (float*)(TA + 16 * TAL);
;   const u16* zr = (const u16*)(p.ws + OFF_R1);
;   const char* wl = p.ws + OFF_W + (size_t)l * W_LAYER;
;   u16* sc = (u16*)(p.ws + OFF_R3);
;   __syncthreads();
;   for (int e = tid; e < 2 * ZR + 7 * 256; e += 256) {
;     float v;
;     if (e < 2 * ZR) v = p.in[I_MU][(size_t)l * 2 * ZR + e];
;     else { const int f = e - 2 * ZR, a = f >> 8, c = f & 255;
;       v = a == 0 ? p.in[I_KK][l * 256 + c] : a < 3 ? p.in[I_W0][(size_t)(l * 2 + a - 1) * 256 + c] : a < 5 ? p.in[I_A0][(size_t)(l * 2 + a - 3) * 256 + c] : p.in[I_KA][(size_t)(l * 2 + a - 5) * 256 + c]; }
;     PV[e] = v;
;   }
.LBB0_762:
	s_or_b64 exec, exec, s[26:27]
	s_cmp_eq_u32 s101, 2
	s_cbranch_scc0 .Ltok_b
	s_mov_b32 s101, 0
	s_waitcnt vmcnt(0) lgkmcnt(0)
	s_branch .LBB0_847
.Ltok_b:
	v_readlane_b32 s24, v255, 3
	s_waitcnt vmcnt(0) lgkmcnt(0)
	v_mov_b32_e32 v58, v163
	s_movk_i32 s20, 0x8ff
	s_movk_i32 s21, 0xa00
	v_readlane_b32 s22, v255, 1
	v_readlane_b32 s23, v255, 2
	v_readlane_b32 s25, v255, 4
	v_readlane_b32 s26, v255, 5
	v_readlane_b32 s27, v255, 6
	s_mov_b32 s46, s2
	v_cmp_gt_i32_e32 vcc, s97, v58
	s_barrier
	s_and_saveexec_b64 s[4:5], vcc
	s_cbranch_execz .LBB0_782
	v_readlane_b32 s0, v253, 15
	v_lshlrev_b32_sdwa v0, v232, v58 dst_sel:DWORD dst_unused:UNUSED_PAD src0_sel:DWORD src1_sel:BYTE_0
	v_readlane_b32 s16, v253, 19
	v_readlane_b32 s1, v253, 16
	v_readlane_b32 s8, v253, 7
	v_readlane_b32 s17, v253, 20
	v_lshl_add_u64 v[6:7], s[0:1], 0, v[0:1]
	v_readlane_b32 s14, v253, 13
	v_readlane_b32 s15, v253, 14
	v_readlane_b32 s0, v254, 45
	v_lshl_add_u64 v[4:5], s[16:17], 0, v[0:1]
	v_lshl_add_u64 v[8:9], s[14:15], 0, v[0:1]
	v_or_b32_sdwa v0, v58, s0 dst_sel:DWORD dst_unused:UNUSED_PAD src0_sel:BYTE_0 src1_sel:DWORD
	v_readlane_b32 s18, v253, 21
	v_readlane_b32 s19, v253, 22
	v_lshlrev_b32_e32 v0, 2, v0
	s_movk_i32 s0, 0xff
	v_lshl_add_u64 v[10:11], s[18:19], 0, v[0:1]
	v_max_i32_e32 v0, 0xf00, v58
	v_sub_u32_e32 v0, v0, v58
	v_add_u32_e32 v0, 0xff, v0
	v_cmp_lt_u32_e32 vcc, s0, v0
	s_mov_b64 s[0:1], -1
	v_mov_b32_e32 v2, v58
	v_readlane_b32 s9, v253, 8
	v_readlane_b32 s10, v253, 9
	v_readlane_b32 s11, v253, 10
	v_readlane_b32 s12, v253, 11
	v_readlane_b32 s13, v253, 12
	s_and_saveexec_b64 s[6:7], vcc
	s_cbranch_execz .LBB0_767
	v_lshrrev_b32_e32 v0, 8, v0
	v_add_u32_e32 v14, 1, v0
	v_and_b32_e32 v15, 0x1fffffe, v14
	v_add_u32_e32 v59, 0x100, v58
	v_mov_b32_e32 v0, 0xd420
	v_mov_b32_e32 v2, v10
	v_mov_b32_e32 v3, v11
	v_lshl_add_u32 v16, v58, 2, v0
	s_mov_b64 s[8:9], 0
	v_mov_b32_e32 v17, v15
	v_mov_b64_e32 v[12:13], v[58:59]
	v_readlane_b32 s10, v254, 58

; __global__ void __launch_bounds__(256, 2) fwd_megakernel(Params pk) {
;     ...
;       case 2: phase_tokA(p, l); phase_tokB(p, l, smem); break;
.LBB0_847:
	s_cmp_eq_u32 s101, 1
	s_cbranch_scc0 .Ltok_end
	s_mov_b32 s101, 2
	s_branch .Ltok_again
